# scan: per-chunk y transpose-reduction renamed onto free registers and interleaved into the first tokens' latency slack (was a serial block after the chunk barrier)
# baseline (speedup 1.0000x reference)
.Lscan_nogload_a:
	s_waitcnt lgkmcnt(1)
	v_pk_mul_f32 v[86:87], v[2:3], v[38:39]
	v_cndmask_b32_e64 v190, v102, v94, s[38:39]
	v_pk_mul_f32 v[78:79], v[2:3], v[34:35]
	v_pk_fma_f32 v[86:87], v[4:5], v[40:41], v[86:87]
	v_cndmask_b32_e64 v182, v94, v102, s[38:39]
	v_pk_mul_f32 v[80:81], v[4:5], v[36:37]
	ds_read_b128 v[38:41], v110 offset:4608
	v_cndmask_b32_e64 v191, v103, v95, s[38:39]
	v_add_f32_e32 v90, v86, v87
	v_pk_fma_f32 v[82:83], v[54:55], v[46:47], v[78:79] op_sel_hi:[0,1,1]
	v_cndmask_b32_e64 v183, v95, v103, s[38:39]
	ds_read_b128 v[34:37], v110 offset:512
	v_add_f32_dpp v90, v90, v90 quad_perm:[1,0,3,2] row_mask:0xf bank_mask:0xf bound_ctrl:1
	v_cndmask_b32_e64 v192, v104, v96, s[38:39]
	v_pk_fma_f32 v[84:85], v[54:55], v[48:49], v[80:81] op_sel_hi:[0,1,1]
	ds_read_b128 v[46:49], v110 offset:12800
	v_cndmask_b32_e64 v184, v96, v104, s[38:39]
	v_add_f32_dpp v90, v90, v90 quad_perm:[2,3,0,1] row_mask:0xf bank_mask:0xf bound_ctrl:1
	ds_read_b32 v54, v111 offset:20992
	v_cndmask_b32_e64 v193, v105, v97, s[38:39]
	v_add_f32_dpp v90, v90, v90 row_half_mirror row_mask:0xf bank_mask:0xf bound_ctrl:1
	s_nop 1
	v_add_f32_dpp v92, v90, v90 row_mirror row_mask:0xf bank_mask:0xf bound_ctrl:1
	v_cndmask_b32_e64 v185, v97, v105, s[38:39]
	v_pk_fma_f32 v[2:3], v[92:93], v[42:43], v[82:83] op_sel_hi:[0,1,1] neg_lo:[1,0,0] neg_hi:[1,0,0]
	v_pk_fma_f32 v[4:5], v[92:93], v[44:45], v[84:85] op_sel_hi:[0,1,1] neg_lo:[1,0,0] neg_hi:[1,0,0]
	v_cndmask_b32_e64 v194, v106, v98, s[38:39]
	ds_read_b128 v[42:45], v110 offset:8704
	v_pk_mul_f32 v[86:87], v[2:3], v[60:61]
	v_cndmask_b32_e64 v186, v98, v106, s[38:39]
	v_pk_mul_f32 v[78:79], v[2:3], v[56:57]
	v_pk_fma_f32 v[86:87], v[4:5], v[62:63], v[86:87]
	v_cndmask_b32_e64 v195, v107, v99, s[38:39]
	v_pk_mul_f32 v[80:81], v[4:5], v[58:59]
	v_pk_mul_f32 v[88:89], v[2:3], v[50:51]
	v_cndmask_b32_e64 v187, v99, v107, s[38:39]
	v_add_f32_e32 v90, v86, v87
	v_pk_fma_f32 v[82:83], v[76:77], v[68:69], v[78:79] op_sel_hi:[0,1,1]
	v_cndmask_b32_e64 v196, v108, v100, s[38:39]
	v_pk_fma_f32 v[88:89], v[4:5], v[52:53], v[88:89]
	v_add_f32_dpp v90, v90, v90 quad_perm:[1,0,3,2] row_mask:0xf bank_mask:0xf bound_ctrl:1
	v_cndmask_b32_e64 v188, v100, v108, s[38:39]
	v_pk_fma_f32 v[84:85], v[76:77], v[70:71], v[80:81] op_sel_hi:[0,1,1]
	ds_read_b128 v[60:63], v110 offset:4864
	v_cndmask_b32_e64 v197, v109, v101, s[38:39]
	v_add_f32_dpp v90, v90, v90 quad_perm:[2,3,0,1] row_mask:0xf bank_mask:0xf bound_ctrl:1
	ds_read_b128 v[56:59], v110 offset:768
	v_cndmask_b32_e64 v189, v101, v109, s[38:39]
	v_add_f32_e32 v94, v88, v89
	v_add_f32_dpp v90, v90, v90 row_half_mirror row_mask:0xf bank_mask:0xf bound_ctrl:1
	v_add_f32_dpp v182, v190, v182 row_ror:8 row_mask:0xf bank_mask:0xf bound_ctrl:1
	ds_read_b128 v[50:53], v110 offset:16896
	ds_read_b128 v[68:71], v110 offset:13056
	v_add_f32_dpp v183, v191, v183 row_ror:8 row_mask:0xf bank_mask:0xf bound_ctrl:1
	v_add_f32_dpp v92, v90, v90 row_mirror row_mask:0xf bank_mask:0xf bound_ctrl:1
	ds_read_b32 v76, v111 offset:21248
	v_add_f32_dpp v184, v192, v184 row_ror:8 row_mask:0xf bank_mask:0xf bound_ctrl:1
	v_pk_fma_f32 v[2:3], v[92:93], v[64:65], v[82:83] op_sel_hi:[0,1,1] neg_lo:[1,0,0] neg_hi:[1,0,0]
	v_pk_fma_f32 v[4:5], v[92:93], v[66:67], v[84:85] op_sel_hi:[0,1,1] neg_lo:[1,0,0] neg_hi:[1,0,0]
	v_add_f32_dpp v185, v193, v185 row_ror:8 row_mask:0xf bank_mask:0xf bound_ctrl:1
	ds_read_b128 v[64:67], v110 offset:8960
	s_waitcnt lgkmcnt(6)
	v_add_f32_dpp v186, v194, v186 row_ror:8 row_mask:0xf bank_mask:0xf bound_ctrl:1
	v_pk_mul_f32 v[86:87], v[2:3], v[38:39]
	v_pk_mul_f32 v[78:79], v[2:3], v[34:35]
	v_add_f32_dpp v187, v195, v187 row_ror:8 row_mask:0xf bank_mask:0xf bound_ctrl:1
	v_pk_fma_f32 v[86:87], v[4:5], v[40:41], v[86:87]
	v_pk_mul_f32 v[80:81], v[4:5], v[36:37]
	v_add_f32_dpp v188, v196, v188 row_ror:8 row_mask:0xf bank_mask:0xf bound_ctrl:1
	v_pk_mul_f32 v[88:89], v[2:3], v[72:73]
	v_add_f32_e32 v90, v86, v87
	v_add_f32_dpp v189, v197, v189 row_ror:8 row_mask:0xf bank_mask:0xf bound_ctrl:1
	v_pk_fma_f32 v[82:83], v[54:55], v[46:47], v[78:79] op_sel_hi:[0,1,1]
	v_pk_fma_f32 v[88:89], v[4:5], v[74:75], v[88:89]
	v_cndmask_b32_e64 v190, v186, v182, s[40:41]
	v_add_f32_dpp v90, v90, v90 quad_perm:[1,0,3,2] row_mask:0xf bank_mask:0xf bound_ctrl:1
	v_pk_fma_f32 v[84:85], v[54:55], v[48:49], v[80:81] op_sel_hi:[0,1,1]
	v_cndmask_b32_e64 v191, v187, v183, s[40:41]
	ds_read_b128 v[38:41], v110 offset:5120
	v_add_f32_dpp v90, v90, v90 quad_perm:[2,3,0,1] row_mask:0xf bank_mask:0xf bound_ctrl:1
	v_cndmask_b32_e64 v192, v188, v184, s[40:41]
	ds_read_b128 v[34:37], v110 offset:1024
	v_add_f32_e32 v95, v88, v89
	v_cndmask_b32_e64 v193, v189, v185, s[40:41]
	v_add_f32_dpp v90, v90, v90 row_half_mirror row_mask:0xf bank_mask:0xf bound_ctrl:1
	ds_read_b128 v[72:75], v110 offset:17152
	v_cndmask_b32_e64 v182, v182, v186, s[40:41]
	ds_read_b128 v[46:49], v110 offset:13312
	v_add_f32_dpp v92, v90, v90 row_mirror row_mask:0xf bank_mask:0xf bound_ctrl:1
	v_cndmask_b32_e64 v183, v183, v187, s[40:41]
	ds_read_b32 v54, v111 offset:21504
	v_pk_fma_f32 v[2:3], v[92:93], v[42:43], v[82:83] op_sel_hi:[0,1,1] neg_lo:[1,0,0] neg_hi:[1,0,0]
	v_cndmask_b32_e64 v184, v184, v188, s[40:41]
	v_pk_fma_f32 v[4:5], v[92:93], v[44:45], v[84:85] op_sel_hi:[0,1,1] neg_lo:[1,0,0] neg_hi:[1,0,0]
	ds_read_b128 v[42:45], v110 offset:9216
	v_cndmask_b32_e64 v185, v185, v189, s[40:41]
	s_waitcnt lgkmcnt(6)
	v_pk_mul_f32 v[86:87], v[2:3], v[60:61]
	v_add_f32_dpp v182, v190, v182 row_half_mirror row_mask:0xf bank_mask:0xf bound_ctrl:1
	v_pk_mul_f32 v[78:79], v[2:3], v[56:57]
	v_pk_fma_f32 v[86:87], v[4:5], v[62:63], v[86:87]
	v_add_f32_dpp v183, v191, v183 row_half_mirror row_mask:0xf bank_mask:0xf bound_ctrl:1
	v_pk_mul_f32 v[80:81], v[4:5], v[58:59]
	v_pk_mul_f32 v[88:89], v[2:3], v[50:51]
	v_add_f32_dpp v184, v192, v184 row_half_mirror row_mask:0xf bank_mask:0xf bound_ctrl:1
	v_add_f32_e32 v90, v86, v87
	v_pk_fma_f32 v[82:83], v[76:77], v[68:69], v[78:79] op_sel_hi:[0,1,1]
	v_add_f32_dpp v185, v193, v185 row_half_mirror row_mask:0xf bank_mask:0xf bound_ctrl:1
	v_pk_fma_f32 v[88:89], v[4:5], v[52:53], v[88:89]
	v_add_f32_dpp v90, v90, v90 quad_perm:[1,0,3,2] row_mask:0xf bank_mask:0xf bound_ctrl:1
	v_cndmask_b32_e64 v190, v184, v182, s[42:43]
	v_pk_fma_f32 v[84:85], v[76:77], v[70:71], v[80:81] op_sel_hi:[0,1,1]
	ds_read_b128 v[60:63], v110 offset:5376
	v_cndmask_b32_e64 v191, v185, v183, s[42:43]
	v_add_f32_dpp v90, v90, v90 quad_perm:[2,3,0,1] row_mask:0xf bank_mask:0xf bound_ctrl:1
	ds_read_b128 v[56:59], v110 offset:1280
	v_cndmask_b32_e64 v182, v182, v184, s[42:43]
	v_add_f32_e32 v96, v88, v89
	v_add_f32_dpp v90, v90, v90 row_half_mirror row_mask:0xf bank_mask:0xf bound_ctrl:1
	v_cndmask_b32_e64 v183, v183, v185, s[42:43]
	ds_read_b128 v[50:53], v110 offset:17408
	ds_read_b128 v[68:71], v110 offset:13568
	v_add_f32_dpp v182, v190, v182 quad_perm:[1,0,3,2] row_mask:0xf bank_mask:0xf bound_ctrl:1
	v_add_f32_dpp v92, v90, v90 row_mirror row_mask:0xf bank_mask:0xf bound_ctrl:1
	ds_read_b32 v76, v111 offset:21760
	v_add_f32_dpp v183, v191, v183 quad_perm:[1,0,3,2] row_mask:0xf bank_mask:0xf bound_ctrl:1
	v_pk_fma_f32 v[2:3], v[92:93], v[64:65], v[82:83] op_sel_hi:[0,1,1] neg_lo:[1,0,0] neg_hi:[1,0,0]
	v_pk_fma_f32 v[4:5], v[92:93], v[66:67], v[84:85] op_sel_hi:[0,1,1] neg_lo:[1,0,0] neg_hi:[1,0,0]
	v_cndmask_b32_e64 v190, v183, v182, s[44:45]
	ds_read_b128 v[64:67], v110 offset:9472
	s_waitcnt lgkmcnt(6)
	v_cndmask_b32_e64 v182, v182, v183, s[44:45]
	v_pk_mul_f32 v[86:87], v[2:3], v[38:39]
	v_pk_mul_f32 v[78:79], v[2:3], v[34:35]
	v_add_f32_dpp v182, v190, v182 quad_perm:[2,3,0,1] row_mask:0xf bank_mask:0xf bound_ctrl:1
	s_cmp_eq_u32 s33, 0
	s_cbranch_scc1 .Lscan_nost_a
	v_lshl_add_u32 v198, v114, 10, v116
	v_add_u32_e32 v114, s34, v114
	global_store_dword v198, v182, s[50:51]
	s_cmp_eq_u32 s33, 16
	s_cbranch_scc0 .Lscan_nost_a
	v_mov_b32_e32 v114, v126
.Lscan_nost_a:
	v_pk_fma_f32 v[86:87], v[4:5], v[40:41], v[86:87]
	v_pk_mul_f32 v[80:81], v[4:5], v[36:37]
	v_pk_mul_f32 v[88:89], v[2:3], v[72:73]
	v_add_f32_e32 v90, v86, v87
	v_pk_fma_f32 v[82:83], v[54:55], v[46:47], v[78:79] op_sel_hi:[0,1,1]
	v_pk_fma_f32 v[88:89], v[4:5], v[74:75], v[88:89]
	v_add_f32_dpp v90, v90, v90 quad_perm:[1,0,3,2] row_mask:0xf bank_mask:0xf bound_ctrl:1
	v_pk_fma_f32 v[84:85], v[54:55], v[48:49], v[80:81] op_sel_hi:[0,1,1]
	ds_read_b128 v[38:41], v110 offset:5632
	v_add_f32_dpp v90, v90, v90 quad_perm:[2,3,0,1] row_mask:0xf bank_mask:0xf bound_ctrl:1
	ds_read_b128 v[34:37], v110 offset:1536
	v_add_f32_e32 v97, v88, v89
	v_add_f32_dpp v90, v90, v90 row_half_mirror row_mask:0xf bank_mask:0xf bound_ctrl:1
	ds_read_b128 v[72:75], v110 offset:17664
	ds_read_b128 v[46:49], v110 offset:13824
	v_add_f32_dpp v92, v90, v90 row_mirror row_mask:0xf bank_mask:0xf bound_ctrl:1
	ds_read_b32 v54, v111 offset:22016
	v_pk_fma_f32 v[2:3], v[92:93], v[42:43], v[82:83] op_sel_hi:[0,1,1] neg_lo:[1,0,0] neg_hi:[1,0,0]
	v_pk_fma_f32 v[4:5], v[92:93], v[44:45], v[84:85] op_sel_hi:[0,1,1] neg_lo:[1,0,0] neg_hi:[1,0,0]
	ds_read_b128 v[42:45], v110 offset:9728
	s_waitcnt lgkmcnt(6)
	v_pk_mul_f32 v[86:87], v[2:3], v[60:61]
	v_pk_mul_f32 v[78:79], v[2:3], v[56:57]
	v_pk_fma_f32 v[86:87], v[4:5], v[62:63], v[86:87]
	v_pk_mul_f32 v[80:81], v[4:5], v[58:59]
	v_pk_mul_f32 v[88:89], v[2:3], v[50:51]
	v_add_f32_e32 v90, v86, v87
	v_pk_fma_f32 v[82:83], v[76:77], v[68:69], v[78:79] op_sel_hi:[0,1,1]
	v_pk_fma_f32 v[88:89], v[4:5], v[52:53], v[88:89]
	v_add_f32_dpp v90, v90, v90 quad_perm:[1,0,3,2] row_mask:0xf bank_mask:0xf bound_ctrl:1
	v_pk_fma_f32 v[84:85], v[76:77], v[70:71], v[80:81] op_sel_hi:[0,1,1]
	ds_read_b128 v[60:63], v110 offset:5888
	v_add_f32_dpp v90, v90, v90 quad_perm:[2,3,0,1] row_mask:0xf bank_mask:0xf bound_ctrl:1
	ds_read_b128 v[56:59], v110 offset:1792
	v_add_f32_e32 v98, v88, v89
	v_add_f32_dpp v90, v90, v90 row_half_mirror row_mask:0xf bank_mask:0xf bound_ctrl:1
	ds_read_b128 v[50:53], v110 offset:17920
	ds_read_b128 v[68:71], v110 offset:14080
	v_add_f32_dpp v92, v90, v90 row_mirror row_mask:0xf bank_mask:0xf bound_ctrl:1
	ds_read_b32 v76, v111 offset:22272
	v_pk_fma_f32 v[2:3], v[92:93], v[64:65], v[82:83] op_sel_hi:[0,1,1] neg_lo:[1,0,0] neg_hi:[1,0,0]
	v_pk_fma_f32 v[4:5], v[92:93], v[66:67], v[84:85] op_sel_hi:[0,1,1] neg_lo:[1,0,0] neg_hi:[1,0,0]
	ds_read_b128 v[64:67], v110 offset:9984
	s_waitcnt lgkmcnt(6)
	v_pk_mul_f32 v[86:87], v[2:3], v[38:39]
	v_pk_mul_f32 v[78:79], v[2:3], v[34:35]
	v_pk_fma_f32 v[86:87], v[4:5], v[40:41], v[86:87]
	v_pk_mul_f32 v[80:81], v[4:5], v[36:37]
	v_pk_mul_f32 v[88:89], v[2:3], v[72:73]
	v_add_f32_e32 v90, v86, v87
	v_pk_fma_f32 v[82:83], v[54:55], v[46:47], v[78:79] op_sel_hi:[0,1,1]
	v_pk_fma_f32 v[88:89], v[4:5], v[74:75], v[88:89]
	v_add_f32_dpp v90, v90, v90 quad_perm:[1,0,3,2] row_mask:0xf bank_mask:0xf bound_ctrl:1
	v_pk_fma_f32 v[84:85], v[54:55], v[48:49], v[80:81] op_sel_hi:[0,1,1]
	ds_read_b128 v[38:41], v110 offset:6144
	v_add_f32_dpp v90, v90, v90 quad_perm:[2,3,0,1] row_mask:0xf bank_mask:0xf bound_ctrl:1
	ds_read_b128 v[34:37], v110 offset:2048
	v_add_f32_e32 v99, v88, v89
	v_add_f32_dpp v90, v90, v90 row_half_mirror row_mask:0xf bank_mask:0xf bound_ctrl:1
	ds_read_b128 v[72:75], v110 offset:18176
	ds_read_b128 v[46:49], v110 offset:14336
	v_add_f32_dpp v92, v90, v90 row_mirror row_mask:0xf bank_mask:0xf bound_ctrl:1
	ds_read_b32 v54, v111 offset:22528
	v_pk_fma_f32 v[2:3], v[92:93], v[42:43], v[82:83] op_sel_hi:[0,1,1] neg_lo:[1,0,0] neg_hi:[1,0,0]
	v_pk_fma_f32 v[4:5], v[92:93], v[44:45], v[84:85] op_sel_hi:[0,1,1] neg_lo:[1,0,0] neg_hi:[1,0,0]
	ds_read_b128 v[42:45], v110 offset:10240
	s_waitcnt lgkmcnt(6)
	v_pk_mul_f32 v[86:87], v[2:3], v[60:61]
	v_pk_mul_f32 v[78:79], v[2:3], v[56:57]
	v_pk_fma_f32 v[86:87], v[4:5], v[62:63], v[86:87]
	v_pk_mul_f32 v[80:81], v[4:5], v[58:59]
	v_pk_mul_f32 v[88:89], v[2:3], v[50:51]
	v_add_f32_e32 v90, v86, v87
	v_pk_fma_f32 v[82:83], v[76:77], v[68:69], v[78:79] op_sel_hi:[0,1,1]
	v_pk_fma_f32 v[88:89], v[4:5], v[52:53], v[88:89]
	v_add_f32_dpp v90, v90, v90 quad_perm:[1,0,3,2] row_mask:0xf bank_mask:0xf bound_ctrl:1
	v_pk_fma_f32 v[84:85], v[76:77], v[70:71], v[80:81] op_sel_hi:[0,1,1]
	ds_read_b128 v[60:63], v110 offset:6400
	v_add_f32_dpp v90, v90, v90 quad_perm:[2,3,0,1] row_mask:0xf bank_mask:0xf bound_ctrl:1
	ds_read_b128 v[56:59], v110 offset:2304
	v_add_f32_e32 v100, v88, v89
	v_add_f32_dpp v90, v90, v90 row_half_mirror row_mask:0xf bank_mask:0xf bound_ctrl:1
	ds_read_b128 v[50:53], v110 offset:18432
	ds_read_b128 v[68:71], v110 offset:14592
	v_add_f32_dpp v92, v90, v90 row_mirror row_mask:0xf bank_mask:0xf bound_ctrl:1
	ds_read_b32 v76, v111 offset:22784
	v_pk_fma_f32 v[2:3], v[92:93], v[64:65], v[82:83] op_sel_hi:[0,1,1] neg_lo:[1,0,0] neg_hi:[1,0,0]
	v_pk_fma_f32 v[4:5], v[92:93], v[66:67], v[84:85] op_sel_hi:[0,1,1] neg_lo:[1,0,0] neg_hi:[1,0,0]
	ds_read_b128 v[64:67], v110 offset:10496
	s_waitcnt lgkmcnt(6)
	v_pk_mul_f32 v[86:87], v[2:3], v[38:39]
	v_pk_mul_f32 v[78:79], v[2:3], v[34:35]
	v_pk_fma_f32 v[86:87], v[4:5], v[40:41], v[86:87]
	v_pk_mul_f32 v[80:81], v[4:5], v[36:37]
	v_pk_mul_f32 v[88:89], v[2:3], v[72:73]
	v_add_f32_e32 v90, v86, v87
	v_pk_fma_f32 v[82:83], v[54:55], v[46:47], v[78:79] op_sel_hi:[0,1,1]
	v_pk_fma_f32 v[88:89], v[4:5], v[74:75], v[88:89]
	v_add_f32_dpp v90, v90, v90 quad_perm:[1,0,3,2] row_mask:0xf bank_mask:0xf bound_ctrl:1
	v_pk_fma_f32 v[84:85], v[54:55], v[48:49], v[80:81] op_sel_hi:[0,1,1]
	ds_read_b128 v[38:41], v110 offset:6656
	v_add_f32_dpp v90, v90, v90 quad_perm:[2,3,0,1] row_mask:0xf bank_mask:0xf bound_ctrl:1
	ds_read_b128 v[34:37], v110 offset:2560
	v_add_f32_e32 v101, v88, v89
	v_add_f32_dpp v90, v90, v90 row_half_mirror row_mask:0xf bank_mask:0xf bound_ctrl:1
	ds_read_b128 v[72:75], v110 offset:18688
	ds_read_b128 v[46:49], v110 offset:14848
	v_add_f32_dpp v92, v90, v90 row_mirror row_mask:0xf bank_mask:0xf bound_ctrl:1
	ds_read_b32 v54, v111 offset:23040
	v_pk_fma_f32 v[2:3], v[92:93], v[42:43], v[82:83] op_sel_hi:[0,1,1] neg_lo:[1,0,0] neg_hi:[1,0,0]
	v_pk_fma_f32 v[4:5], v[92:93], v[44:45], v[84:85] op_sel_hi:[0,1,1] neg_lo:[1,0,0] neg_hi:[1,0,0]
	ds_read_b128 v[42:45], v110 offset:10752
	s_waitcnt lgkmcnt(6)
	v_pk_mul_f32 v[86:87], v[2:3], v[60:61]
	v_pk_mul_f32 v[78:79], v[2:3], v[56:57]
	v_pk_fma_f32 v[86:87], v[4:5], v[62:63], v[86:87]
	v_pk_mul_f32 v[80:81], v[4:5], v[58:59]
	v_pk_mul_f32 v[88:89], v[2:3], v[50:51]
	v_add_f32_e32 v90, v86, v87
	v_pk_fma_f32 v[82:83], v[76:77], v[68:69], v[78:79] op_sel_hi:[0,1,1]
	v_pk_fma_f32 v[88:89], v[4:5], v[52:53], v[88:89]
	v_add_f32_dpp v90, v90, v90 quad_perm:[1,0,3,2] row_mask:0xf bank_mask:0xf bound_ctrl:1
	v_pk_fma_f32 v[84:85], v[76:77], v[70:71], v[80:81] op_sel_hi:[0,1,1]
	ds_read_b128 v[60:63], v110 offset:6912
	v_add_f32_dpp v90, v90, v90 quad_perm:[2,3,0,1] row_mask:0xf bank_mask:0xf bound_ctrl:1
	ds_read_b128 v[56:59], v110 offset:2816
	v_add_f32_e32 v102, v88, v89
	v_add_f32_dpp v90, v90, v90 row_half_mirror row_mask:0xf bank_mask:0xf bound_ctrl:1
	ds_read_b128 v[50:53], v110 offset:18944
	ds_read_b128 v[68:71], v110 offset:15104
	v_add_f32_dpp v92, v90, v90 row_mirror row_mask:0xf bank_mask:0xf bound_ctrl:1
	ds_read_b32 v76, v111 offset:23296
	v_pk_fma_f32 v[2:3], v[92:93], v[64:65], v[82:83] op_sel_hi:[0,1,1] neg_lo:[1,0,0] neg_hi:[1,0,0]
	v_pk_fma_f32 v[4:5], v[92:93], v[66:67], v[84:85] op_sel_hi:[0,1,1] neg_lo:[1,0,0] neg_hi:[1,0,0]
	ds_read_b128 v[64:67], v110 offset:11008
	s_waitcnt lgkmcnt(6)
	v_pk_mul_f32 v[86:87], v[2:3], v[38:39]
	v_pk_mul_f32 v[78:79], v[2:3], v[34:35]
	v_pk_fma_f32 v[86:87], v[4:5], v[40:41], v[86:87]
	v_pk_mul_f32 v[80:81], v[4:5], v[36:37]
	v_pk_mul_f32 v[88:89], v[2:3], v[72:73]
	v_add_f32_e32 v90, v86, v87
	v_pk_fma_f32 v[82:83], v[54:55], v[46:47], v[78:79] op_sel_hi:[0,1,1]
	v_pk_fma_f32 v[88:89], v[4:5], v[74:75], v[88:89]
	v_add_f32_dpp v90, v90, v90 quad_perm:[1,0,3,2] row_mask:0xf bank_mask:0xf bound_ctrl:1
	v_pk_fma_f32 v[84:85], v[54:55], v[48:49], v[80:81] op_sel_hi:[0,1,1]
	ds_read_b128 v[38:41], v110 offset:7168
	v_add_f32_dpp v90, v90, v90 quad_perm:[2,3,0,1] row_mask:0xf bank_mask:0xf bound_ctrl:1
	ds_read_b128 v[34:37], v110 offset:3072
	v_add_f32_e32 v103, v88, v89
	v_add_f32_dpp v90, v90, v90 row_half_mirror row_mask:0xf bank_mask:0xf bound_ctrl:1
	ds_read_b128 v[72:75], v110 offset:19200
	ds_read_b128 v[46:49], v110 offset:15360
	v_add_f32_dpp v92, v90, v90 row_mirror row_mask:0xf bank_mask:0xf bound_ctrl:1
	ds_read_b32 v54, v111 offset:23552
	v_pk_fma_f32 v[2:3], v[92:93], v[42:43], v[82:83] op_sel_hi:[0,1,1] neg_lo:[1,0,0] neg_hi:[1,0,0]
	v_pk_fma_f32 v[4:5], v[92:93], v[44:45], v[84:85] op_sel_hi:[0,1,1] neg_lo:[1,0,0] neg_hi:[1,0,0]
	ds_read_b128 v[42:45], v110 offset:11264
	s_waitcnt lgkmcnt(6)
	v_pk_mul_f32 v[86:87], v[2:3], v[60:61]
	v_pk_mul_f32 v[78:79], v[2:3], v[56:57]
	v_pk_fma_f32 v[86:87], v[4:5], v[62:63], v[86:87]
	v_pk_mul_f32 v[80:81], v[4:5], v[58:59]
	v_pk_mul_f32 v[88:89], v[2:3], v[50:51]
	v_add_f32_e32 v90, v86, v87
	v_pk_fma_f32 v[82:83], v[76:77], v[68:69], v[78:79] op_sel_hi:[0,1,1]
	v_pk_fma_f32 v[88:89], v[4:5], v[52:53], v[88:89]
	v_add_f32_dpp v90, v90, v90 quad_perm:[1,0,3,2] row_mask:0xf bank_mask:0xf bound_ctrl:1
	v_pk_fma_f32 v[84:85], v[76:77], v[70:71], v[80:81] op_sel_hi:[0,1,1]
	ds_read_b128 v[60:63], v110 offset:7424
	v_add_f32_dpp v90, v90, v90 quad_perm:[2,3,0,1] row_mask:0xf bank_mask:0xf bound_ctrl:1
	ds_read_b128 v[56:59], v110 offset:3328
	v_add_f32_e32 v104, v88, v89
	v_add_f32_dpp v90, v90, v90 row_half_mirror row_mask:0xf bank_mask:0xf bound_ctrl:1
	ds_read_b128 v[50:53], v110 offset:19456
	ds_read_b128 v[68:71], v110 offset:15616
	v_add_f32_dpp v92, v90, v90 row_mirror row_mask:0xf bank_mask:0xf bound_ctrl:1
	ds_read_b32 v76, v111 offset:23808
	v_pk_fma_f32 v[2:3], v[92:93], v[64:65], v[82:83] op_sel_hi:[0,1,1] neg_lo:[1,0,0] neg_hi:[1,0,0]
	v_pk_fma_f32 v[4:5], v[92:93], v[66:67], v[84:85] op_sel_hi:[0,1,1] neg_lo:[1,0,0] neg_hi:[1,0,0]
	ds_read_b128 v[64:67], v110 offset:11520
	s_waitcnt lgkmcnt(6)
	v_pk_mul_f32 v[86:87], v[2:3], v[38:39]
	v_pk_mul_f32 v[78:79], v[2:3], v[34:35]
	v_pk_fma_f32 v[86:87], v[4:5], v[40:41], v[86:87]
	v_pk_mul_f32 v[80:81], v[4:5], v[36:37]
	v_pk_mul_f32 v[88:89], v[2:3], v[72:73]
	v_add_f32_e32 v90, v86, v87
	v_pk_fma_f32 v[82:83], v[54:55], v[46:47], v[78:79] op_sel_hi:[0,1,1]
	v_pk_fma_f32 v[88:89], v[4:5], v[74:75], v[88:89]
	v_add_f32_dpp v90, v90, v90 quad_perm:[1,0,3,2] row_mask:0xf bank_mask:0xf bound_ctrl:1
	v_pk_fma_f32 v[84:85], v[54:55], v[48:49], v[80:81] op_sel_hi:[0,1,1]
	ds_read_b128 v[38:41], v110 offset:7680
	v_add_f32_dpp v90, v90, v90 quad_perm:[2,3,0,1] row_mask:0xf bank_mask:0xf bound_ctrl:1
	ds_read_b128 v[34:37], v110 offset:3584
	v_add_f32_e32 v105, v88, v89
	v_add_f32_dpp v90, v90, v90 row_half_mirror row_mask:0xf bank_mask:0xf bound_ctrl:1
	ds_read_b128 v[72:75], v110 offset:19712
	ds_read_b128 v[46:49], v110 offset:15872
	v_add_f32_dpp v92, v90, v90 row_mirror row_mask:0xf bank_mask:0xf bound_ctrl:1
	ds_read_b32 v54, v111 offset:24064
	v_pk_fma_f32 v[2:3], v[92:93], v[42:43], v[82:83] op_sel_hi:[0,1,1] neg_lo:[1,0,0] neg_hi:[1,0,0]
	v_pk_fma_f32 v[4:5], v[92:93], v[44:45], v[84:85] op_sel_hi:[0,1,1] neg_lo:[1,0,0] neg_hi:[1,0,0]
	ds_read_b128 v[42:45], v110 offset:11776
	s_waitcnt lgkmcnt(6)
	v_pk_mul_f32 v[86:87], v[2:3], v[60:61]
	v_pk_mul_f32 v[78:79], v[2:3], v[56:57]
	v_pk_fma_f32 v[86:87], v[4:5], v[62:63], v[86:87]
	v_pk_mul_f32 v[80:81], v[4:5], v[58:59]
	v_pk_mul_f32 v[88:89], v[2:3], v[50:51]
	v_add_f32_e32 v90, v86, v87
	v_pk_fma_f32 v[82:83], v[76:77], v[68:69], v[78:79] op_sel_hi:[0,1,1]
	v_pk_fma_f32 v[88:89], v[4:5], v[52:53], v[88:89]
	v_add_f32_dpp v90, v90, v90 quad_perm:[1,0,3,2] row_mask:0xf bank_mask:0xf bound_ctrl:1
	v_pk_fma_f32 v[84:85], v[76:77], v[70:71], v[80:81] op_sel_hi:[0,1,1]
	ds_read_b128 v[60:63], v110 offset:7936
	v_add_f32_dpp v90, v90, v90 quad_perm:[2,3,0,1] row_mask:0xf bank_mask:0xf bound_ctrl:1
	ds_read_b128 v[56:59], v110 offset:3840
	v_add_f32_e32 v106, v88, v89
	v_add_f32_dpp v90, v90, v90 row_half_mirror row_mask:0xf bank_mask:0xf bound_ctrl:1
	ds_read_b128 v[50:53], v110 offset:19968
	ds_read_b128 v[68:71], v110 offset:16128
	v_add_f32_dpp v92, v90, v90 row_mirror row_mask:0xf bank_mask:0xf bound_ctrl:1
	ds_read_b32 v76, v111 offset:24320
	s_cmpk_eq_i32 s33, 0x10f
	s_cbranch_scc1 .Lscan_tail_last
	v_pk_fma_f32 v[2:3], v[92:93], v[64:65], v[82:83] op_sel_hi:[0,1,1] neg_lo:[1,0,0] neg_hi:[1,0,0]
	v_pk_fma_f32 v[4:5], v[92:93], v[66:67], v[84:85] op_sel_hi:[0,1,1] neg_lo:[1,0,0] neg_hi:[1,0,0]
	ds_read_b128 v[64:67], v110 offset:12032
	s_waitcnt lgkmcnt(6)
	v_pk_mul_f32 v[86:87], v[2:3], v[38:39]
	v_pk_mul_f32 v[78:79], v[2:3], v[34:35]
	v_pk_fma_f32 v[86:87], v[4:5], v[40:41], v[86:87]
	v_pk_mul_f32 v[80:81], v[4:5], v[36:37]
	v_pk_mul_f32 v[88:89], v[2:3], v[72:73]
	v_add_f32_e32 v90, v86, v87
	v_pk_fma_f32 v[82:83], v[54:55], v[46:47], v[78:79] op_sel_hi:[0,1,1]
	v_pk_fma_f32 v[88:89], v[4:5], v[74:75], v[88:89]
	v_add_f32_dpp v90, v90, v90 quad_perm:[1,0,3,2] row_mask:0xf bank_mask:0xf bound_ctrl:1
	v_pk_fma_f32 v[84:85], v[54:55], v[48:49], v[80:81] op_sel_hi:[0,1,1]
	s_waitcnt vmcnt(6)
	v_add_f32_dpp v90, v90, v90 quad_perm:[2,3,0,1] row_mask:0xf bank_mask:0xf bound_ctrl:1
	v_pk_add_f32 v[122:123], v[150:151], -1.0 op_sel_hi:[1,0]
	v_add_f32_e32 v107, v88, v89
	v_add_f32_dpp v90, v90, v90 row_half_mirror row_mask:0xf bank_mask:0xf bound_ctrl:1
	ds_read_b128 v[72:75], v110 offset:20224
	v_pk_add_f32 v[124:125], v[152:153], -1.0 op_sel_hi:[1,0]
	v_add_f32_dpp v92, v90, v90 row_mirror row_mask:0xf bank_mask:0xf bound_ctrl:1
	v_pk_mul_f32 v[118:119], v[154:155], v[150:151]
	v_pk_fma_f32 v[2:3], v[92:93], v[42:43], v[82:83] op_sel_hi:[0,1,1] neg_lo:[1,0,0] neg_hi:[1,0,0]
	v_pk_fma_f32 v[4:5], v[92:93], v[44:45], v[84:85] op_sel_hi:[0,1,1] neg_lo:[1,0,0] neg_hi:[1,0,0]
	v_pk_fma_f32 v[122:123], v[6:7], v[122:123], 1.0 op_sel_hi:[1,1,0]
	s_waitcnt lgkmcnt(1)
	v_pk_mul_f32 v[86:87], v[2:3], v[60:61]
	v_pk_mul_f32 v[78:79], v[2:3], v[56:57]
	v_pk_fma_f32 v[86:87], v[4:5], v[62:63], v[86:87]
	v_pk_mul_f32 v[80:81], v[4:5], v[58:59]
	v_pk_mul_f32 v[88:89], v[2:3], v[50:51]
	v_add_f32_e32 v90, v86, v87
	v_pk_fma_f32 v[82:83], v[76:77], v[68:69], v[78:79] op_sel_hi:[0,1,1]
	v_pk_fma_f32 v[88:89], v[4:5], v[52:53], v[88:89]
	v_add_f32_dpp v90, v90, v90 quad_perm:[1,0,3,2] row_mask:0xf bank_mask:0xf bound_ctrl:1
	v_pk_fma_f32 v[84:85], v[76:77], v[70:71], v[80:81] op_sel_hi:[0,1,1]
	v_pk_fma_f32 v[124:125], v[8:9], v[124:125], 1.0 op_sel_hi:[1,1,0]
	v_add_f32_dpp v90, v90, v90 quad_perm:[2,3,0,1] row_mask:0xf bank_mask:0xf bound_ctrl:1
	v_pk_mul_f32 v[120:121], v[156:157], v[152:153]
	v_add_f32_e32 v108, v88, v89
	v_add_f32_dpp v90, v90, v90 row_half_mirror row_mask:0xf bank_mask:0xf bound_ctrl:1
	v_pk_mul_f32 v[122:123], v[138:139], v[122:123]
	v_pk_mul_f32 v[124:125], v[140:141], v[124:125]
	v_add_f32_dpp v92, v90, v90 row_mirror row_mask:0xf bank_mask:0xf bound_ctrl:1
	ds_write_b128 v112, v[146:149] offset:0
	ds_write_b128 v112, v[154:157] offset:4096
	v_pk_fma_f32 v[2:3], v[92:93], v[64:65], v[82:83] op_sel_hi:[0,1,1] neg_lo:[1,0,0] neg_hi:[1,0,0]
	v_pk_fma_f32 v[4:5], v[92:93], v[66:67], v[84:85] op_sel_hi:[0,1,1] neg_lo:[1,0,0] neg_hi:[1,0,0]
	ds_write_b128 v112, v[134:137] offset:16384
	s_waitcnt lgkmcnt(3)
	v_pk_mul_f32 v[88:89], v[2:3], v[72:73]
	ds_write_b128 v112, v[142:145] offset:20480
	v_pk_fma_f32 v[88:89], v[4:5], v[74:75], v[88:89]
	ds_write_b128 v112, v[118:121] offset:8192
	v_add_f32_e32 v109, v88, v89
	ds_write_b128 v112, v[122:125] offset:12288
	s_waitcnt lgkmcnt(0)
	v_xor_b32_e32 v110, 0x6000, v110
	v_xor_b32_e32 v111, 0x6000, v111
	v_xor_b32_e32 v112, 0x6000, v112
	s_add_i32 s33, s33, 1
	s_barrier
	ds_read_b128 v[38:41], v110 offset:4096
	ds_read_b128 v[34:37], v110 offset:0
	ds_read_b128 v[46:49], v110 offset:12288
	ds_read_b32 v54, v111 offset:20480
	ds_read_b128 v[42:45], v110 offset:8192
	ds_read_b128 v[50:53], v110 offset:16384
	ds_read_b128 v[60:63], v110 offset:4352
	ds_read_b128 v[56:59], v110 offset:256
	ds_read_b128 v[68:71], v110 offset:12544
	ds_read_b32 v76, v111 offset:20736
	ds_read_b128 v[64:67], v110 offset:8448
	ds_read_b128 v[72:75], v110 offset:16640
	s_cmpk_ge_i32 s33, 0x10e
	s_cbranch_scc1 .Lscan_skipload_b
	v_mul_u32_u24_e32 v0, 0xf00, v113
	v_lshl_add_u32 v125, v113, 10, v115
	v_add_u32_e32 v0, v0, v115
	v_add_u32_e32 v113, s34, v113
	global_load_dwordx4 v[146:149], v125, s[46:47]
	global_load_dwordx4 v[150:153], v125, s[48:49]
	global_load_dwordx4 v[154:157], v125, s[22:23]
	global_load_dwordx4 v[138:141], v0, s[12:13] offset:1024
	global_load_dwordx4 v[134:137], v0, s[12:13]
	global_load_dwordx4 v[142:145], v0, s[12:13] offset:2048
	s_cmp_eq_u32 s33, 13
	s_cbranch_scc0 .Lscan_nogload_b
	v_mov_b32_e32 v113, v117
	s_branch .Lscan_nogload_b

.Lscan_nost_b:
	v_pk_fma_f32 v[86:87], v[4:5], v[40:41], v[86:87]
	v_pk_mul_f32 v[80:81], v[4:5], v[36:37]
	v_pk_mul_f32 v[88:89], v[2:3], v[72:73]
	v_add_f32_e32 v90, v86, v87
	v_pk_fma_f32 v[82:83], v[54:55], v[46:47], v[78:79] op_sel_hi:[0,1,1]
	v_pk_fma_f32 v[88:89], v[4:5], v[74:75], v[88:89]
	v_add_f32_dpp v90, v90, v90 quad_perm:[1,0,3,2] row_mask:0xf bank_mask:0xf bound_ctrl:1
	v_pk_fma_f32 v[84:85], v[54:55], v[48:49], v[80:81] op_sel_hi:[0,1,1]
	ds_read_b128 v[38:41], v110 offset:5632
	v_add_f32_dpp v90, v90, v90 quad_perm:[2,3,0,1] row_mask:0xf bank_mask:0xf bound_ctrl:1
	ds_read_b128 v[34:37], v110 offset:1536
	v_add_f32_e32 v97, v88, v89
	v_add_f32_dpp v90, v90, v90 row_half_mirror row_mask:0xf bank_mask:0xf bound_ctrl:1
	ds_read_b128 v[72:75], v110 offset:17664
	ds_read_b128 v[46:49], v110 offset:13824
	v_add_f32_dpp v92, v90, v90 row_mirror row_mask:0xf bank_mask:0xf bound_ctrl:1
	ds_read_b32 v54, v111 offset:22016
	v_pk_fma_f32 v[2:3], v[92:93], v[42:43], v[82:83] op_sel_hi:[0,1,1] neg_lo:[1,0,0] neg_hi:[1,0,0]
	v_pk_fma_f32 v[4:5], v[92:93], v[44:45], v[84:85] op_sel_hi:[0,1,1] neg_lo:[1,0,0] neg_hi:[1,0,0]
	ds_read_b128 v[42:45], v110 offset:9728
	s_waitcnt lgkmcnt(6)
	v_pk_mul_f32 v[86:87], v[2:3], v[60:61]
	v_pk_mul_f32 v[78:79], v[2:3], v[56:57]
	v_pk_fma_f32 v[86:87], v[4:5], v[62:63], v[86:87]
	v_pk_mul_f32 v[80:81], v[4:5], v[58:59]
	v_pk_mul_f32 v[88:89], v[2:3], v[50:51]
	v_add_f32_e32 v90, v86, v87
	v_pk_fma_f32 v[82:83], v[76:77], v[68:69], v[78:79] op_sel_hi:[0,1,1]
	v_pk_fma_f32 v[88:89], v[4:5], v[52:53], v[88:89]
	v_add_f32_dpp v90, v90, v90 quad_perm:[1,0,3,2] row_mask:0xf bank_mask:0xf bound_ctrl:1
	v_pk_fma_f32 v[84:85], v[76:77], v[70:71], v[80:81] op_sel_hi:[0,1,1]
	ds_read_b128 v[60:63], v110 offset:5888
	v_add_f32_dpp v90, v90, v90 quad_perm:[2,3,0,1] row_mask:0xf bank_mask:0xf bound_ctrl:1
	ds_read_b128 v[56:59], v110 offset:1792
	v_add_f32_e32 v98, v88, v89
	v_add_f32_dpp v90, v90, v90 row_half_mirror row_mask:0xf bank_mask:0xf bound_ctrl:1
	ds_read_b128 v[50:53], v110 offset:17920
	ds_read_b128 v[68:71], v110 offset:14080
	v_add_f32_dpp v92, v90, v90 row_mirror row_mask:0xf bank_mask:0xf bound_ctrl:1
	ds_read_b32 v76, v111 offset:22272
	v_pk_fma_f32 v[2:3], v[92:93], v[64:65], v[82:83] op_sel_hi:[0,1,1] neg_lo:[1,0,0] neg_hi:[1,0,0]
	v_pk_fma_f32 v[4:5], v[92:93], v[66:67], v[84:85] op_sel_hi:[0,1,1] neg_lo:[1,0,0] neg_hi:[1,0,0]
	ds_read_b128 v[64:67], v110 offset:9984
	s_waitcnt lgkmcnt(6)
	v_pk_mul_f32 v[86:87], v[2:3], v[38:39]
	v_pk_mul_f32 v[78:79], v[2:3], v[34:35]
	v_pk_fma_f32 v[86:87], v[4:5], v[40:41], v[86:87]
	v_pk_mul_f32 v[80:81], v[4:5], v[36:37]
	v_pk_mul_f32 v[88:89], v[2:3], v[72:73]
	v_add_f32_e32 v90, v86, v87
	v_pk_fma_f32 v[82:83], v[54:55], v[46:47], v[78:79] op_sel_hi:[0,1,1]
	v_pk_fma_f32 v[88:89], v[4:5], v[74:75], v[88:89]
	v_add_f32_dpp v90, v90, v90 quad_perm:[1,0,3,2] row_mask:0xf bank_mask:0xf bound_ctrl:1
	v_pk_fma_f32 v[84:85], v[54:55], v[48:49], v[80:81] op_sel_hi:[0,1,1]
	ds_read_b128 v[38:41], v110 offset:6144
	v_add_f32_dpp v90, v90, v90 quad_perm:[2,3,0,1] row_mask:0xf bank_mask:0xf bound_ctrl:1
	ds_read_b128 v[34:37], v110 offset:2048
	v_add_f32_e32 v99, v88, v89
	v_add_f32_dpp v90, v90, v90 row_half_mirror row_mask:0xf bank_mask:0xf bound_ctrl:1
	ds_read_b128 v[72:75], v110 offset:18176
	ds_read_b128 v[46:49], v110 offset:14336
	v_add_f32_dpp v92, v90, v90 row_mirror row_mask:0xf bank_mask:0xf bound_ctrl:1
	ds_read_b32 v54, v111 offset:22528
	v_pk_fma_f32 v[2:3], v[92:93], v[42:43], v[82:83] op_sel_hi:[0,1,1] neg_lo:[1,0,0] neg_hi:[1,0,0]
	v_pk_fma_f32 v[4:5], v[92:93], v[44:45], v[84:85] op_sel_hi:[0,1,1] neg_lo:[1,0,0] neg_hi:[1,0,0]
	ds_read_b128 v[42:45], v110 offset:10240
	s_waitcnt lgkmcnt(6)
	v_pk_mul_f32 v[86:87], v[2:3], v[60:61]
	v_pk_mul_f32 v[78:79], v[2:3], v[56:57]
	v_pk_fma_f32 v[86:87], v[4:5], v[62:63], v[86:87]
	v_pk_mul_f32 v[80:81], v[4:5], v[58:59]
	v_pk_mul_f32 v[88:89], v[2:3], v[50:51]
	v_add_f32_e32 v90, v86, v87
	v_pk_fma_f32 v[82:83], v[76:77], v[68:69], v[78:79] op_sel_hi:[0,1,1]
	v_pk_fma_f32 v[88:89], v[4:5], v[52:53], v[88:89]
	v_add_f32_dpp v90, v90, v90 quad_perm:[1,0,3,2] row_mask:0xf bank_mask:0xf bound_ctrl:1
	v_pk_fma_f32 v[84:85], v[76:77], v[70:71], v[80:81] op_sel_hi:[0,1,1]
	ds_read_b128 v[60:63], v110 offset:6400
	v_add_f32_dpp v90, v90, v90 quad_perm:[2,3,0,1] row_mask:0xf bank_mask:0xf bound_ctrl:1
	ds_read_b128 v[56:59], v110 offset:2304
	v_add_f32_e32 v100, v88, v89
	v_add_f32_dpp v90, v90, v90 row_half_mirror row_mask:0xf bank_mask:0xf bound_ctrl:1
	ds_read_b128 v[50:53], v110 offset:18432
	ds_read_b128 v[68:71], v110 offset:14592
	v_add_f32_dpp v92, v90, v90 row_mirror row_mask:0xf bank_mask:0xf bound_ctrl:1
	ds_read_b32 v76, v111 offset:22784
	v_pk_fma_f32 v[2:3], v[92:93], v[64:65], v[82:83] op_sel_hi:[0,1,1] neg_lo:[1,0,0] neg_hi:[1,0,0]
	v_pk_fma_f32 v[4:5], v[92:93], v[66:67], v[84:85] op_sel_hi:[0,1,1] neg_lo:[1,0,0] neg_hi:[1,0,0]
	ds_read_b128 v[64:67], v110 offset:10496
	s_waitcnt lgkmcnt(6)
	v_pk_mul_f32 v[86:87], v[2:3], v[38:39]
	v_pk_mul_f32 v[78:79], v[2:3], v[34:35]
	v_pk_fma_f32 v[86:87], v[4:5], v[40:41], v[86:87]
	v_pk_mul_f32 v[80:81], v[4:5], v[36:37]
	v_pk_mul_f32 v[88:89], v[2:3], v[72:73]
	v_add_f32_e32 v90, v86, v87
	v_pk_fma_f32 v[82:83], v[54:55], v[46:47], v[78:79] op_sel_hi:[0,1,1]
	v_pk_fma_f32 v[88:89], v[4:5], v[74:75], v[88:89]
	v_add_f32_dpp v90, v90, v90 quad_perm:[1,0,3,2] row_mask:0xf bank_mask:0xf bound_ctrl:1
	v_pk_fma_f32 v[84:85], v[54:55], v[48:49], v[80:81] op_sel_hi:[0,1,1]
	ds_read_b128 v[38:41], v110 offset:6656
	v_add_f32_dpp v90, v90, v90 quad_perm:[2,3,0,1] row_mask:0xf bank_mask:0xf bound_ctrl:1
	ds_read_b128 v[34:37], v110 offset:2560
	v_add_f32_e32 v101, v88, v89
	v_add_f32_dpp v90, v90, v90 row_half_mirror row_mask:0xf bank_mask:0xf bound_ctrl:1
	ds_read_b128 v[72:75], v110 offset:18688
	ds_read_b128 v[46:49], v110 offset:14848
	v_add_f32_dpp v92, v90, v90 row_mirror row_mask:0xf bank_mask:0xf bound_ctrl:1
	ds_read_b32 v54, v111 offset:23040
	v_pk_fma_f32 v[2:3], v[92:93], v[42:43], v[82:83] op_sel_hi:[0,1,1] neg_lo:[1,0,0] neg_hi:[1,0,0]
	v_pk_fma_f32 v[4:5], v[92:93], v[44:45], v[84:85] op_sel_hi:[0,1,1] neg_lo:[1,0,0] neg_hi:[1,0,0]
	ds_read_b128 v[42:45], v110 offset:10752
	s_waitcnt lgkmcnt(6)
	v_pk_mul_f32 v[86:87], v[2:3], v[60:61]
	v_pk_mul_f32 v[78:79], v[2:3], v[56:57]
	v_pk_fma_f32 v[86:87], v[4:5], v[62:63], v[86:87]
	v_pk_mul_f32 v[80:81], v[4:5], v[58:59]
	v_pk_mul_f32 v[88:89], v[2:3], v[50:51]
	v_add_f32_e32 v90, v86, v87
	v_pk_fma_f32 v[82:83], v[76:77], v[68:69], v[78:79] op_sel_hi:[0,1,1]
	v_pk_fma_f32 v[88:89], v[4:5], v[52:53], v[88:89]
	v_add_f32_dpp v90, v90, v90 quad_perm:[1,0,3,2] row_mask:0xf bank_mask:0xf bound_ctrl:1
	v_pk_fma_f32 v[84:85], v[76:77], v[70:71], v[80:81] op_sel_hi:[0,1,1]
	ds_read_b128 v[60:63], v110 offset:6912
	v_add_f32_dpp v90, v90, v90 quad_perm:[2,3,0,1] row_mask:0xf bank_mask:0xf bound_ctrl:1
	ds_read_b128 v[56:59], v110 offset:2816
	v_add_f32_e32 v102, v88, v89
	v_add_f32_dpp v90, v90, v90 row_half_mirror row_mask:0xf bank_mask:0xf bound_ctrl:1
	ds_read_b128 v[50:53], v110 offset:18944
	ds_read_b128 v[68:71], v110 offset:15104
	v_add_f32_dpp v92, v90, v90 row_mirror row_mask:0xf bank_mask:0xf bound_ctrl:1
	ds_read_b32 v76, v111 offset:23296
	v_pk_fma_f32 v[2:3], v[92:93], v[64:65], v[82:83] op_sel_hi:[0,1,1] neg_lo:[1,0,0] neg_hi:[1,0,0]
	v_pk_fma_f32 v[4:5], v[92:93], v[66:67], v[84:85] op_sel_hi:[0,1,1] neg_lo:[1,0,0] neg_hi:[1,0,0]
	ds_read_b128 v[64:67], v110 offset:11008
	s_waitcnt lgkmcnt(6)
	v_pk_mul_f32 v[86:87], v[2:3], v[38:39]
	v_pk_mul_f32 v[78:79], v[2:3], v[34:35]
	v_pk_fma_f32 v[86:87], v[4:5], v[40:41], v[86:87]
	v_pk_mul_f32 v[80:81], v[4:5], v[36:37]
	v_pk_mul_f32 v[88:89], v[2:3], v[72:73]
	v_add_f32_e32 v90, v86, v87
	v_pk_fma_f32 v[82:83], v[54:55], v[46:47], v[78:79] op_sel_hi:[0,1,1]
	v_pk_fma_f32 v[88:89], v[4:5], v[74:75], v[88:89]
	v_add_f32_dpp v90, v90, v90 quad_perm:[1,0,3,2] row_mask:0xf bank_mask:0xf bound_ctrl:1
	v_pk_fma_f32 v[84:85], v[54:55], v[48:49], v[80:81] op_sel_hi:[0,1,1]
	ds_read_b128 v[38:41], v110 offset:7168
	v_add_f32_dpp v90, v90, v90 quad_perm:[2,3,0,1] row_mask:0xf bank_mask:0xf bound_ctrl:1
	ds_read_b128 v[34:37], v110 offset:3072
	v_add_f32_e32 v103, v88, v89
	v_add_f32_dpp v90, v90, v90 row_half_mirror row_mask:0xf bank_mask:0xf bound_ctrl:1
	ds_read_b128 v[72:75], v110 offset:19200
	ds_read_b128 v[46:49], v110 offset:15360
	v_add_f32_dpp v92, v90, v90 row_mirror row_mask:0xf bank_mask:0xf bound_ctrl:1
	ds_read_b32 v54, v111 offset:23552
	v_pk_fma_f32 v[2:3], v[92:93], v[42:43], v[82:83] op_sel_hi:[0,1,1] neg_lo:[1,0,0] neg_hi:[1,0,0]
	v_pk_fma_f32 v[4:5], v[92:93], v[44:45], v[84:85] op_sel_hi:[0,1,1] neg_lo:[1,0,0] neg_hi:[1,0,0]
	ds_read_b128 v[42:45], v110 offset:11264
	s_waitcnt lgkmcnt(6)
	v_pk_mul_f32 v[86:87], v[2:3], v[60:61]
	v_pk_mul_f32 v[78:79], v[2:3], v[56:57]
	v_pk_fma_f32 v[86:87], v[4:5], v[62:63], v[86:87]
	v_pk_mul_f32 v[80:81], v[4:5], v[58:59]
	v_pk_mul_f32 v[88:89], v[2:3], v[50:51]
	v_add_f32_e32 v90, v86, v87
	v_pk_fma_f32 v[82:83], v[76:77], v[68:69], v[78:79] op_sel_hi:[0,1,1]
	v_pk_fma_f32 v[88:89], v[4:5], v[52:53], v[88:89]
	v_add_f32_dpp v90, v90, v90 quad_perm:[1,0,3,2] row_mask:0xf bank_mask:0xf bound_ctrl:1
	v_pk_fma_f32 v[84:85], v[76:77], v[70:71], v[80:81] op_sel_hi:[0,1,1]
	ds_read_b128 v[60:63], v110 offset:7424
	v_add_f32_dpp v90, v90, v90 quad_perm:[2,3,0,1] row_mask:0xf bank_mask:0xf bound_ctrl:1
	ds_read_b128 v[56:59], v110 offset:3328
	v_add_f32_e32 v104, v88, v89
	v_add_f32_dpp v90, v90, v90 row_half_mirror row_mask:0xf bank_mask:0xf bound_ctrl:1
	ds_read_b128 v[50:53], v110 offset:19456
	ds_read_b128 v[68:71], v110 offset:15616
	v_add_f32_dpp v92, v90, v90 row_mirror row_mask:0xf bank_mask:0xf bound_ctrl:1
	ds_read_b32 v76, v111 offset:23808
	v_pk_fma_f32 v[2:3], v[92:93], v[64:65], v[82:83] op_sel_hi:[0,1,1] neg_lo:[1,0,0] neg_hi:[1,0,0]
	v_pk_fma_f32 v[4:5], v[92:93], v[66:67], v[84:85] op_sel_hi:[0,1,1] neg_lo:[1,0,0] neg_hi:[1,0,0]
	ds_read_b128 v[64:67], v110 offset:11520
	s_waitcnt lgkmcnt(6)
	v_pk_mul_f32 v[86:87], v[2:3], v[38:39]
	v_pk_mul_f32 v[78:79], v[2:3], v[34:35]
	v_pk_fma_f32 v[86:87], v[4:5], v[40:41], v[86:87]
	v_pk_mul_f32 v[80:81], v[4:5], v[36:37]
	v_pk_mul_f32 v[88:89], v[2:3], v[72:73]
	v_add_f32_e32 v90, v86, v87
	v_pk_fma_f32 v[82:83], v[54:55], v[46:47], v[78:79] op_sel_hi:[0,1,1]
	v_pk_fma_f32 v[88:89], v[4:5], v[74:75], v[88:89]
	v_add_f32_dpp v90, v90, v90 quad_perm:[1,0,3,2] row_mask:0xf bank_mask:0xf bound_ctrl:1
	v_pk_fma_f32 v[84:85], v[54:55], v[48:49], v[80:81] op_sel_hi:[0,1,1]
	ds_read_b128 v[38:41], v110 offset:7680
	v_add_f32_dpp v90, v90, v90 quad_perm:[2,3,0,1] row_mask:0xf bank_mask:0xf bound_ctrl:1
	ds_read_b128 v[34:37], v110 offset:3584
	v_add_f32_e32 v105, v88, v89
	v_add_f32_dpp v90, v90, v90 row_half_mirror row_mask:0xf bank_mask:0xf bound_ctrl:1
	ds_read_b128 v[72:75], v110 offset:19712
	ds_read_b128 v[46:49], v110 offset:15872
	v_add_f32_dpp v92, v90, v90 row_mirror row_mask:0xf bank_mask:0xf bound_ctrl:1
	ds_read_b32 v54, v111 offset:24064
	v_pk_fma_f32 v[2:3], v[92:93], v[42:43], v[82:83] op_sel_hi:[0,1,1] neg_lo:[1,0,0] neg_hi:[1,0,0]
	v_pk_fma_f32 v[4:5], v[92:93], v[44:45], v[84:85] op_sel_hi:[0,1,1] neg_lo:[1,0,0] neg_hi:[1,0,0]
	ds_read_b128 v[42:45], v110 offset:11776
	s_waitcnt lgkmcnt(6)
	v_pk_mul_f32 v[86:87], v[2:3], v[60:61]
	v_pk_mul_f32 v[78:79], v[2:3], v[56:57]
	v_pk_fma_f32 v[86:87], v[4:5], v[62:63], v[86:87]
	v_pk_mul_f32 v[80:81], v[4:5], v[58:59]
	v_pk_mul_f32 v[88:89], v[2:3], v[50:51]
	v_add_f32_e32 v90, v86, v87
	v_pk_fma_f32 v[82:83], v[76:77], v[68:69], v[78:79] op_sel_hi:[0,1,1]
	v_pk_fma_f32 v[88:89], v[4:5], v[52:53], v[88:89]
	v_add_f32_dpp v90, v90, v90 quad_perm:[1,0,3,2] row_mask:0xf bank_mask:0xf bound_ctrl:1
	v_pk_fma_f32 v[84:85], v[76:77], v[70:71], v[80:81] op_sel_hi:[0,1,1]
	ds_read_b128 v[60:63], v110 offset:7936
	v_add_f32_dpp v90, v90, v90 quad_perm:[2,3,0,1] row_mask:0xf bank_mask:0xf bound_ctrl:1
	ds_read_b128 v[56:59], v110 offset:3840
	v_add_f32_e32 v106, v88, v89
	v_add_f32_dpp v90, v90, v90 row_half_mirror row_mask:0xf bank_mask:0xf bound_ctrl:1
	ds_read_b128 v[50:53], v110 offset:19968
	ds_read_b128 v[68:71], v110 offset:16128
	v_add_f32_dpp v92, v90, v90 row_mirror row_mask:0xf bank_mask:0xf bound_ctrl:1
	ds_read_b32 v76, v111 offset:24320
	s_cmpk_eq_i32 s33, 0x10f
	s_cbranch_scc1 .Lscan_tail_last
	v_pk_fma_f32 v[2:3], v[92:93], v[64:65], v[82:83] op_sel_hi:[0,1,1] neg_lo:[1,0,0] neg_hi:[1,0,0]
	v_pk_fma_f32 v[4:5], v[92:93], v[66:67], v[84:85] op_sel_hi:[0,1,1] neg_lo:[1,0,0] neg_hi:[1,0,0]
	ds_read_b128 v[64:67], v110 offset:12032
	s_waitcnt lgkmcnt(6)
	v_pk_mul_f32 v[86:87], v[2:3], v[38:39]
	v_pk_mul_f32 v[78:79], v[2:3], v[34:35]
	v_pk_fma_f32 v[86:87], v[4:5], v[40:41], v[86:87]
	v_pk_mul_f32 v[80:81], v[4:5], v[36:37]
	v_pk_mul_f32 v[88:89], v[2:3], v[72:73]
	v_add_f32_e32 v90, v86, v87
	v_pk_fma_f32 v[82:83], v[54:55], v[46:47], v[78:79] op_sel_hi:[0,1,1]
	v_pk_fma_f32 v[88:89], v[4:5], v[74:75], v[88:89]
	v_add_f32_dpp v90, v90, v90 quad_perm:[1,0,3,2] row_mask:0xf bank_mask:0xf bound_ctrl:1
	v_pk_fma_f32 v[84:85], v[54:55], v[48:49], v[80:81] op_sel_hi:[0,1,1]
	s_waitcnt vmcnt(6)
	v_add_f32_dpp v90, v90, v90 quad_perm:[2,3,0,1] row_mask:0xf bank_mask:0xf bound_ctrl:1
	v_pk_add_f32 v[122:123], v[26:27], -1.0 op_sel_hi:[1,0]
	v_add_f32_e32 v107, v88, v89
	v_add_f32_dpp v90, v90, v90 row_half_mirror row_mask:0xf bank_mask:0xf bound_ctrl:1
	ds_read_b128 v[72:75], v110 offset:20224
	v_pk_add_f32 v[124:125], v[28:29], -1.0 op_sel_hi:[1,0]
	v_add_f32_dpp v92, v90, v90 row_mirror row_mask:0xf bank_mask:0xf bound_ctrl:1
	v_pk_mul_f32 v[118:119], v[30:31], v[26:27]
	v_pk_fma_f32 v[2:3], v[92:93], v[42:43], v[82:83] op_sel_hi:[0,1,1] neg_lo:[1,0,0] neg_hi:[1,0,0]
	v_pk_fma_f32 v[4:5], v[92:93], v[44:45], v[84:85] op_sel_hi:[0,1,1] neg_lo:[1,0,0] neg_hi:[1,0,0]
	v_pk_fma_f32 v[122:123], v[6:7], v[122:123], 1.0 op_sel_hi:[1,1,0]
	s_waitcnt lgkmcnt(1)
	v_pk_mul_f32 v[86:87], v[2:3], v[60:61]
	v_pk_mul_f32 v[78:79], v[2:3], v[56:57]
	v_pk_fma_f32 v[86:87], v[4:5], v[62:63], v[86:87]
	v_pk_mul_f32 v[80:81], v[4:5], v[58:59]
	v_pk_mul_f32 v[88:89], v[2:3], v[50:51]
	v_add_f32_e32 v90, v86, v87
	v_pk_fma_f32 v[82:83], v[76:77], v[68:69], v[78:79] op_sel_hi:[0,1,1]
	v_pk_fma_f32 v[88:89], v[4:5], v[52:53], v[88:89]
	v_add_f32_dpp v90, v90, v90 quad_perm:[1,0,3,2] row_mask:0xf bank_mask:0xf bound_ctrl:1
	v_pk_fma_f32 v[84:85], v[76:77], v[70:71], v[80:81] op_sel_hi:[0,1,1]
	v_pk_fma_f32 v[124:125], v[8:9], v[124:125], 1.0 op_sel_hi:[1,1,0]
	v_add_f32_dpp v90, v90, v90 quad_perm:[2,3,0,1] row_mask:0xf bank_mask:0xf bound_ctrl:1
	v_pk_mul_f32 v[120:121], v[32:33], v[28:29]
	v_add_f32_e32 v108, v88, v89
	v_add_f32_dpp v90, v90, v90 row_half_mirror row_mask:0xf bank_mask:0xf bound_ctrl:1
	v_pk_mul_f32 v[122:123], v[14:15], v[122:123]
	v_pk_mul_f32 v[124:125], v[16:17], v[124:125]
	v_add_f32_dpp v92, v90, v90 row_mirror row_mask:0xf bank_mask:0xf bound_ctrl:1
	ds_write_b128 v112, v[22:25] offset:0
	ds_write_b128 v112, v[30:33] offset:4096
	v_pk_fma_f32 v[2:3], v[92:93], v[64:65], v[82:83] op_sel_hi:[0,1,1] neg_lo:[1,0,0] neg_hi:[1,0,0]
	v_pk_fma_f32 v[4:5], v[92:93], v[66:67], v[84:85] op_sel_hi:[0,1,1] neg_lo:[1,0,0] neg_hi:[1,0,0]
	ds_write_b128 v112, v[10:13] offset:16384
	s_waitcnt lgkmcnt(3)
	v_pk_mul_f32 v[88:89], v[2:3], v[72:73]
	ds_write_b128 v112, v[18:21] offset:20480
	v_pk_fma_f32 v[88:89], v[4:5], v[74:75], v[88:89]
	ds_write_b128 v112, v[118:121] offset:8192
	v_add_f32_e32 v109, v88, v89
	ds_write_b128 v112, v[122:125] offset:12288
	s_waitcnt lgkmcnt(0)
	v_xor_b32_e32 v110, 0x6000, v110
	v_xor_b32_e32 v111, 0x6000, v111
	v_xor_b32_e32 v112, 0x6000, v112
	s_add_i32 s33, s33, 1
	s_barrier
	s_branch .Lscan_chunk
